# group-local barriers only at the six alias-safe seams (after steps 0,4,5,7,11,12); seams 1,6,8 kept global because the next phase overlays other groups ACT rows
# baseline (speedup 1.0000x reference)
.LBB0_515:
	s_waitcnt vmcnt(0)
	s_waitcnt vmcnt(0) lgkmcnt(0)
	s_barrier
	s_and_saveexec_b64 s[0:1], s[62:63]
	s_cbranch_execz .LBB0_202
	v_readlane_b32 s8, v254, 49
	s_mov_b32 s9, 0x18b1
	s_nop 0
	s_lshr_b32 s12, s9, s8
	s_and_b32 s12, s12, s100
	s_and_b32 s12, s12, 1
	s_cmp_eq_u32 s12, 0
	s_cbranch_scc1 .Lgbar
	s_lshl_b32 s12, 2, s8
	s_sub_i32 s12, s12, 1
	s_and_b32 s12, s12, s9
	s_bcnt1_i32_b32 s12, s12
	s_lshl_b32 s9, s12, 5
	v_readlane_b32 s8, v252, 0
	v_readlane_b32 s10, v252, 45
	v_readlane_b32 s11, v252, 46
	s_and_b32 s8, s8, 7
	s_lshl_b32 s8, s8, 6
	s_add_u32 s8, s8, 0xe3600
	s_add_u32 s10, s10, s8
	s_addc_u32 s11, s11, 0
	v_mov_b32_e32 v1, 1
	v_mov_b32_e32 v2, 0
	global_atomic_add v2, v1, s[10:11]
	s_mov_b32 s12, 0
